# P6 and P8 epilogues: sector-coalescing lane-group transposes for x/xb loads and bf16 xb stores
# speedup vs baseline: 1.0096x; 1.0041x over previous
.LBB0_1373:
	v_and_b32_e32 v236, 48, v144
	v_mul_u32_u24_e32 v232, 3, v236
	v_sub_u32_e32 v232, 0, v232
	v_ashrrev_i32_e32 v233, 31, v232
	v_sub_u32_e32 v236, 0, v236
	v_ashrrev_i32_e32 v237, 31, v236
	v_lshl_add_u32 v140, s30, 8, v142
	v_ashrrev_i32_e32 v141, 31, v140
	v_readlane_b32 s60, v240, 5
	v_lshl_or_b32 v138, s8, 8, v144
	v_lshlrev_b64 v[150:151], 12, v[140:141]
	v_readlane_b32 s61, v240, 6
	v_ashrrev_i32_e32 v139, 31, v138
	v_xor_b32_e32 v149, 16, v148
	v_lshl_add_u64 v[150:151], s[60:61], 0, v[150:151]
	v_lshl_add_u64 v[150:151], v[138:139], 2, v[150:151]
	v_lshl_add_u64 v[234:235], v[150:151], 0, v[232:233]
	global_load_dwordx4 v[152:155], v[234:235], off
	global_load_dwordx4 v[156:159], v[234:235], off offset:64
	global_load_dwordx4 v[160:163], v[234:235], off offset:128
	global_load_dwordx4 v[164:167], v[234:235], off offset:192
	v_and_b32_e32 v150, 64, v148
	v_add_u32_e32 v150, 64, v150
	v_cmp_lt_i32_e32 vcc, v149, v150
	v_xor_b32_e32 v151, 32, v148
	v_lshlrev_b64 v[168:169], 11, v[140:141]
	v_cndmask_b32_e32 v149, v148, v149, vcc
	v_cmp_lt_i32_e32 vcc, v151, v150
	v_lshlrev_b32_e32 v150, 2, v149
	s_lshl_b32 s30, s8, 2
	v_cndmask_b32_e32 v151, v148, v151, vcc
	v_lshlrev_b32_e32 v149, 2, v151
	v_lshl_add_u64 v[168:169], s[12:13], 0, v[168:169]
	s_ashr_i32 s31, s30, 31
	v_lshl_add_u64 v[168:169], v[138:139], 1, v[168:169]
	v_readlane_b32 s62, v240, 7
	v_readlane_b32 s63, v240, 8
	s_waitcnt vmcnt(0)
	v_permlane16_swap_b32_e32 v152, v156
	v_permlane16_swap_b32_e32 v153, v157
	v_permlane16_swap_b32_e32 v154, v158
	v_permlane16_swap_b32_e32 v155, v159
	v_permlane16_swap_b32_e32 v160, v164
	v_permlane16_swap_b32_e32 v161, v165
	v_permlane16_swap_b32_e32 v162, v166
	v_permlane16_swap_b32_e32 v163, v167
	v_permlane32_swap_b32_e32 v152, v160
	v_permlane32_swap_b32_e32 v153, v161
	v_permlane32_swap_b32_e32 v154, v162
	v_permlane32_swap_b32_e32 v155, v163
	v_permlane32_swap_b32_e32 v156, v164
	v_permlane32_swap_b32_e32 v157, v165
	v_permlane32_swap_b32_e32 v158, v166
	v_permlane32_swap_b32_e32 v159, v167
	v_pk_add_f32 v[120:121], v[120:121], v[152:153]
	v_pk_add_f32 v[122:123], v[122:123], v[154:155]
	v_pk_add_f32 v[152:153], v[118:119], v[162:163]
	v_pk_add_f32 v[118:119], v[116:117], v[160:161]
	v_pk_mul_f32 v[116:117], v[120:121], v[120:121]
	v_pk_add_f32 v[124:125], v[124:125], v[156:157]
	v_pk_add_f32 v[154:155], v[114:115], v[166:167]
	v_pk_add_f32 v[156:157], v[112:113], v[164:165]
	v_pk_mul_f32 v[112:113], v[122:123], v[122:123]
	v_add_f32_e32 v115, v116, v117
	v_add_f32_e32 v112, v112, v115
	v_pk_mul_f32 v[160:161], v[124:125], v[124:125]
	v_add_f32_e32 v112, v113, v112
	v_pk_add_f32 v[126:127], v[126:127], v[158:159]
	v_add_f32_e32 v112, v160, v112
	v_pk_mul_f32 v[158:159], v[126:127], v[126:127]
	v_add_f32_e32 v112, v161, v112
	v_add_f32_e32 v112, v158, v112
	v_pk_mul_f32 v[164:165], v[118:119], v[118:119]
	v_add_f32_e32 v112, v159, v112
	v_add_f32_e32 v112, v164, v112
	v_pk_mul_f32 v[162:163], v[152:153], v[152:153]
	v_add_f32_e32 v112, v165, v112
	v_add_f32_e32 v112, v162, v112
	v_pk_mul_f32 v[170:171], v[156:157], v[156:157]
	v_add_f32_e32 v112, v163, v112
	v_add_f32_e32 v112, v170, v112
	v_pk_mul_f32 v[166:167], v[154:155], v[154:155]
	v_add_f32_e32 v112, v171, v112
	v_add_f32_e32 v112, v166, v112
	v_add_f32_e32 v112, v167, v112
	ds_bpermute_b32 v113, v150, v112
	v_cvt_pk_bf16_f32 v114, v120, v121
	v_cvt_pk_bf16_f32 v115, v122, v123
	v_cvt_pk_bf16_f32 v116, v124, v125
	v_cvt_pk_bf16_f32 v117, v126, v127
	s_waitcnt lgkmcnt(0)
	v_add_f32_e32 v112, v112, v113
	ds_bpermute_b32 v113, v149, v112
	v_cvt_pk_bf16_f32 v118, v118, v119
	v_cvt_pk_bf16_f32 v119, v152, v153
	v_cvt_pk_bf16_f32 v120, v156, v157
	v_cvt_pk_bf16_f32 v121, v154, v155
	s_nop 1
	v_permlane16_swap_b32_e32 v114, v118
	v_permlane16_swap_b32_e32 v115, v119
	v_permlane16_swap_b32_e32 v116, v120
	v_permlane16_swap_b32_e32 v117, v121
	v_permlane32_swap_b32_e32 v114, v118
	v_permlane32_swap_b32_e32 v115, v119
	v_permlane32_swap_b32_e32 v116, v120
	v_permlane32_swap_b32_e32 v117, v121
	v_lshl_add_u64 v[238:239], v[168:169], 0, v[236:237]
	global_store_dwordx4 v[238:239], v[114:117], off
	global_store_dwordx4 v[238:239], v[118:121], off offset:64
	s_and_saveexec_b64 s[4:5], s[6:7]
	s_cbranch_execz .LBB0_1375
	v_lshlrev_b64 v[114:115], 6, v[140:141]
	v_lshl_add_u64 v[114:115], s[14:15], 0, v[114:115]
	v_lshl_add_u64 v[114:115], s[30:31], 2, v[114:115]
	s_lshl_b32 s8, s46, 2
	v_lshl_add_u64 v[114:115], v[114:115], 0, s[8:9]
	s_waitcnt lgkmcnt(0)
	v_add_f32_e32 v112, v112, v113
	global_store_dword v[114:115], v112, off
.LBB0_1375:
	s_or_b64 exec, exec, s[4:5]
	v_or_b32_e32 v112, 16, v140
	s_waitcnt lgkmcnt(0)
	v_ashrrev_i32_e32 v113, 31, v112
	v_readlane_b32 s60, v240, 5
	v_lshlrev_b64 v[114:115], 12, v[112:113]
	v_readlane_b32 s61, v240, 6
	v_readlane_b32 s62, v240, 7
	v_readlane_b32 s63, v240, 8
	v_lshl_add_u64 v[114:115], s[60:61], 0, v[114:115]
	v_lshl_add_u64 v[126:127], v[138:139], 2, v[114:115]
	v_lshl_add_u64 v[234:235], v[126:127], 0, v[232:233]
	global_load_dwordx4 v[114:117], v[234:235], off
	global_load_dwordx4 v[118:121], v[234:235], off offset:64
	global_load_dwordx4 v[122:125], v[234:235], off offset:128
	global_load_dwordx4 v[152:155], v[234:235], off offset:192
	v_lshlrev_b64 v[126:127], 11, v[112:113]
	v_lshl_add_u64 v[126:127], s[12:13], 0, v[126:127]
	v_lshl_add_u64 v[126:127], v[138:139], 1, v[126:127]
	s_waitcnt vmcnt(0)
	v_permlane16_swap_b32_e32 v114, v118
	v_permlane16_swap_b32_e32 v115, v119
	v_permlane16_swap_b32_e32 v116, v120
	v_permlane16_swap_b32_e32 v117, v121
	v_permlane16_swap_b32_e32 v122, v152
	v_permlane16_swap_b32_e32 v123, v153
	v_permlane16_swap_b32_e32 v124, v154
	v_permlane16_swap_b32_e32 v125, v155
	v_permlane32_swap_b32_e32 v114, v122
	v_permlane32_swap_b32_e32 v115, v123
	v_permlane32_swap_b32_e32 v116, v124
	v_permlane32_swap_b32_e32 v117, v125
	v_permlane32_swap_b32_e32 v118, v152
	v_permlane32_swap_b32_e32 v119, v153
	v_permlane32_swap_b32_e32 v120, v154
	v_permlane32_swap_b32_e32 v121, v155
	v_pk_add_f32 v[108:109], v[108:109], v[114:115]
	v_pk_add_f32 v[110:111], v[110:111], v[116:117]
	s_waitcnt vmcnt(1)
	v_pk_add_f32 v[114:115], v[102:103], v[124:125]
	v_pk_add_f32 v[102:103], v[100:101], v[122:123]
	v_pk_mul_f32 v[100:101], v[108:109], v[108:109]
	v_pk_add_f32 v[104:105], v[104:105], v[118:119]
	s_waitcnt vmcnt(0)
	v_pk_add_f32 v[116:117], v[98:99], v[154:155]
	v_pk_add_f32 v[118:119], v[96:97], v[152:153]
	v_pk_mul_f32 v[96:97], v[110:111], v[110:111]
	v_add_f32_e32 v99, v100, v101
	v_add_f32_e32 v96, v96, v99
	v_pk_mul_f32 v[122:123], v[104:105], v[104:105]
	v_add_f32_e32 v96, v97, v96
	v_pk_add_f32 v[106:107], v[106:107], v[120:121]
	v_add_f32_e32 v96, v122, v96
	v_pk_mul_f32 v[120:121], v[106:107], v[106:107]
	v_add_f32_e32 v96, v123, v96
	v_add_f32_e32 v96, v120, v96
	v_pk_mul_f32 v[152:153], v[102:103], v[102:103]
	v_add_f32_e32 v96, v121, v96
	v_add_f32_e32 v96, v152, v96
	v_pk_mul_f32 v[124:125], v[114:115], v[114:115]
	v_add_f32_e32 v96, v153, v96
	v_add_f32_e32 v96, v124, v96
	v_pk_mul_f32 v[156:157], v[118:119], v[118:119]
	v_add_f32_e32 v96, v125, v96
	v_add_f32_e32 v96, v156, v96
	v_pk_mul_f32 v[154:155], v[116:117], v[116:117]
	v_add_f32_e32 v96, v157, v96
	v_add_f32_e32 v96, v154, v96
	v_add_f32_e32 v96, v155, v96
	ds_bpermute_b32 v97, v150, v96
	v_cvt_pk_bf16_f32 v98, v108, v109
	v_cvt_pk_bf16_f32 v99, v110, v111
	v_cvt_pk_bf16_f32 v100, v104, v105
	v_cvt_pk_bf16_f32 v101, v106, v107
	s_waitcnt lgkmcnt(0)
	v_add_f32_e32 v96, v96, v97
	ds_bpermute_b32 v97, v149, v96
	v_cvt_pk_bf16_f32 v102, v102, v103
	v_cvt_pk_bf16_f32 v103, v114, v115
	v_cvt_pk_bf16_f32 v104, v118, v119
	v_cvt_pk_bf16_f32 v105, v116, v117
	s_nop 1
	v_permlane16_swap_b32_e32 v98, v102
	v_permlane16_swap_b32_e32 v99, v103
	v_permlane16_swap_b32_e32 v100, v104
	v_permlane16_swap_b32_e32 v101, v105
	v_permlane32_swap_b32_e32 v98, v102
	v_permlane32_swap_b32_e32 v99, v103
	v_permlane32_swap_b32_e32 v100, v104
	v_permlane32_swap_b32_e32 v101, v105
	v_lshl_add_u64 v[238:239], v[126:127], 0, v[236:237]
	global_store_dwordx4 v[238:239], v[98:101], off
	global_store_dwordx4 v[238:239], v[102:105], off offset:64
	s_and_saveexec_b64 s[4:5], s[6:7]
	s_cbranch_execz .LBB0_1377
	v_lshlrev_b64 v[98:99], 6, v[112:113]
	v_lshl_add_u64 v[98:99], s[14:15], 0, v[98:99]
	v_lshl_add_u64 v[98:99], s[30:31], 2, v[98:99]
	s_lshl_b32 s8, s46, 2
	v_lshl_add_u64 v[98:99], v[98:99], 0, s[8:9]
	s_waitcnt lgkmcnt(0)
	v_add_f32_e32 v96, v96, v97
	global_store_dword v[98:99], v96, off
.LBB0_1377:
	s_or_b64 exec, exec, s[4:5]
	v_or_b32_e32 v96, 32, v140
	s_waitcnt lgkmcnt(0)
	v_ashrrev_i32_e32 v97, 31, v96
	v_readlane_b32 s60, v240, 5
	v_lshlrev_b64 v[98:99], 12, v[96:97]
	v_readlane_b32 s61, v240, 6
	v_lshlrev_b64 v[114:115], 11, v[96:97]
	v_lshl_add_u64 v[114:115], s[12:13], 0, v[114:115]
	v_lshl_add_u64 v[98:99], s[60:61], 0, v[98:99]
	v_lshl_add_u64 v[110:111], v[138:139], 2, v[98:99]
	v_lshl_add_u64 v[234:235], v[110:111], 0, v[232:233]
	global_load_dwordx4 v[98:101], v[234:235], off
	global_load_dwordx4 v[102:105], v[234:235], off offset:64
	global_load_dwordx4 v[106:109], v[234:235], off offset:128
	s_nop 0
	global_load_dwordx4 v[110:113], v[234:235], off offset:192
	v_lshl_add_u64 v[114:115], v[138:139], 1, v[114:115]
	v_readlane_b32 s62, v240, 7
	v_readlane_b32 s63, v240, 8
	s_waitcnt vmcnt(0)
	v_permlane16_swap_b32_e32 v98, v102
	v_permlane16_swap_b32_e32 v99, v103
	v_permlane16_swap_b32_e32 v100, v104
	v_permlane16_swap_b32_e32 v101, v105
	v_permlane16_swap_b32_e32 v106, v110
	v_permlane16_swap_b32_e32 v107, v111
	v_permlane16_swap_b32_e32 v108, v112
	v_permlane16_swap_b32_e32 v109, v113
	v_permlane32_swap_b32_e32 v98, v106
	v_permlane32_swap_b32_e32 v99, v107
	v_permlane32_swap_b32_e32 v100, v108
	v_permlane32_swap_b32_e32 v101, v109
	v_permlane32_swap_b32_e32 v102, v110
	v_permlane32_swap_b32_e32 v103, v111
	v_permlane32_swap_b32_e32 v104, v112
	v_permlane32_swap_b32_e32 v105, v113
	v_pk_add_f32 v[92:93], v[92:93], v[98:99]
	v_pk_add_f32 v[94:95], v[94:95], v[100:101]
	s_waitcnt vmcnt(1)
	v_pk_add_f32 v[98:99], v[86:87], v[108:109]
	v_pk_add_f32 v[86:87], v[84:85], v[106:107]
	v_pk_mul_f32 v[84:85], v[92:93], v[92:93]
	v_pk_add_f32 v[88:89], v[88:89], v[102:103]
	s_waitcnt vmcnt(0)
	v_pk_add_f32 v[100:101], v[82:83], v[112:113]
	v_pk_add_f32 v[102:103], v[80:81], v[110:111]
	v_pk_mul_f32 v[80:81], v[94:95], v[94:95]
	v_add_f32_e32 v83, v84, v85
	v_add_f32_e32 v80, v80, v83
	v_pk_mul_f32 v[106:107], v[88:89], v[88:89]
	v_add_f32_e32 v80, v81, v80
	v_pk_add_f32 v[90:91], v[90:91], v[104:105]
	v_add_f32_e32 v80, v106, v80
	v_pk_mul_f32 v[104:105], v[90:91], v[90:91]
	v_add_f32_e32 v80, v107, v80
	v_add_f32_e32 v80, v104, v80
	v_pk_mul_f32 v[110:111], v[86:87], v[86:87]
	v_add_f32_e32 v80, v105, v80
	v_add_f32_e32 v80, v110, v80
	v_pk_mul_f32 v[108:109], v[98:99], v[98:99]
	v_add_f32_e32 v80, v111, v80
	v_add_f32_e32 v80, v108, v80
	v_pk_mul_f32 v[116:117], v[102:103], v[102:103]
	v_add_f32_e32 v80, v109, v80
	v_add_f32_e32 v80, v116, v80
	v_pk_mul_f32 v[112:113], v[100:101], v[100:101]
	v_add_f32_e32 v80, v117, v80
	v_add_f32_e32 v80, v112, v80
	v_add_f32_e32 v80, v113, v80
	ds_bpermute_b32 v81, v150, v80
	v_cvt_pk_bf16_f32 v82, v92, v93
	v_cvt_pk_bf16_f32 v83, v94, v95
	v_cvt_pk_bf16_f32 v84, v88, v89
	v_cvt_pk_bf16_f32 v85, v90, v91
	s_waitcnt lgkmcnt(0)
	v_add_f32_e32 v80, v80, v81
	ds_bpermute_b32 v81, v149, v80
	v_cvt_pk_bf16_f32 v86, v86, v87
	v_cvt_pk_bf16_f32 v87, v98, v99
	v_cvt_pk_bf16_f32 v88, v102, v103
	v_cvt_pk_bf16_f32 v89, v100, v101
	s_nop 1
	v_permlane16_swap_b32_e32 v82, v86
	v_permlane16_swap_b32_e32 v83, v87
	v_permlane16_swap_b32_e32 v84, v88
	v_permlane16_swap_b32_e32 v85, v89
	v_permlane32_swap_b32_e32 v82, v86
	v_permlane32_swap_b32_e32 v83, v87
	v_permlane32_swap_b32_e32 v84, v88
	v_permlane32_swap_b32_e32 v85, v89
	v_lshl_add_u64 v[238:239], v[114:115], 0, v[236:237]
	global_store_dwordx4 v[238:239], v[82:85], off
	global_store_dwordx4 v[238:239], v[86:89], off offset:64
	s_and_saveexec_b64 s[4:5], s[6:7]
	s_cbranch_execz .LBB0_1379
	v_lshlrev_b64 v[82:83], 6, v[96:97]
	v_lshl_add_u64 v[82:83], s[14:15], 0, v[82:83]
	v_lshl_add_u64 v[82:83], s[30:31], 2, v[82:83]
	s_lshl_b32 s8, s46, 2
	v_lshl_add_u64 v[82:83], v[82:83], 0, s[8:9]
	s_waitcnt lgkmcnt(0)
	v_add_f32_e32 v80, v80, v81
	global_store_dword v[82:83], v80, off
.LBB0_1379:
	s_or_b64 exec, exec, s[4:5]
	v_or_b32_e32 v80, 48, v140
	s_waitcnt lgkmcnt(0)
	v_ashrrev_i32_e32 v81, 31, v80
	v_readlane_b32 s60, v240, 5
	v_lshlrev_b64 v[82:83], 12, v[80:81]
	v_readlane_b32 s61, v240, 6
	v_lshlrev_b64 v[98:99], 11, v[80:81]
	v_lshl_add_u64 v[98:99], s[12:13], 0, v[98:99]
	v_lshl_add_u64 v[82:83], s[60:61], 0, v[82:83]
	v_lshl_add_u64 v[94:95], v[138:139], 2, v[82:83]
	v_lshl_add_u64 v[234:235], v[94:95], 0, v[232:233]
	global_load_dwordx4 v[82:85], v[234:235], off
	global_load_dwordx4 v[86:89], v[234:235], off offset:64
	global_load_dwordx4 v[90:93], v[234:235], off offset:128
	s_nop 0
	global_load_dwordx4 v[94:97], v[234:235], off offset:192
	v_lshl_add_u64 v[98:99], v[138:139], 1, v[98:99]
	v_readlane_b32 s62, v240, 7
	v_readlane_b32 s63, v240, 8
	s_waitcnt vmcnt(0)
	v_permlane16_swap_b32_e32 v82, v86
	v_permlane16_swap_b32_e32 v83, v87
	v_permlane16_swap_b32_e32 v84, v88
	v_permlane16_swap_b32_e32 v85, v89
	v_permlane16_swap_b32_e32 v90, v94
	v_permlane16_swap_b32_e32 v91, v95
	v_permlane16_swap_b32_e32 v92, v96
	v_permlane16_swap_b32_e32 v93, v97
	v_permlane32_swap_b32_e32 v82, v90
	v_permlane32_swap_b32_e32 v83, v91
	v_permlane32_swap_b32_e32 v84, v92
	v_permlane32_swap_b32_e32 v85, v93
	v_permlane32_swap_b32_e32 v86, v94
	v_permlane32_swap_b32_e32 v87, v95
	v_permlane32_swap_b32_e32 v88, v96
	v_permlane32_swap_b32_e32 v89, v97
	v_pk_add_f32 v[76:77], v[76:77], v[82:83]
	v_pk_add_f32 v[78:79], v[78:79], v[84:85]
	s_waitcnt vmcnt(1)
	v_pk_add_f32 v[82:83], v[70:71], v[92:93]
	v_pk_add_f32 v[70:71], v[68:69], v[90:91]
	v_pk_mul_f32 v[68:69], v[76:77], v[76:77]
	v_pk_add_f32 v[72:73], v[72:73], v[86:87]
	s_waitcnt vmcnt(0)
	v_pk_add_f32 v[84:85], v[66:67], v[96:97]
	v_pk_add_f32 v[86:87], v[64:65], v[94:95]
	v_pk_mul_f32 v[64:65], v[78:79], v[78:79]
	v_add_f32_e32 v67, v68, v69
	v_add_f32_e32 v64, v64, v67
	v_pk_mul_f32 v[90:91], v[72:73], v[72:73]
	v_add_f32_e32 v64, v65, v64
	v_pk_add_f32 v[74:75], v[74:75], v[88:89]
	v_add_f32_e32 v64, v90, v64
	v_pk_mul_f32 v[88:89], v[74:75], v[74:75]
	v_add_f32_e32 v64, v91, v64
	v_add_f32_e32 v64, v88, v64
	v_pk_mul_f32 v[94:95], v[70:71], v[70:71]
	v_add_f32_e32 v64, v89, v64
	v_add_f32_e32 v64, v94, v64
	v_pk_mul_f32 v[92:93], v[82:83], v[82:83]
	v_add_f32_e32 v64, v95, v64
	v_add_f32_e32 v64, v92, v64
	v_pk_mul_f32 v[100:101], v[86:87], v[86:87]
	v_add_f32_e32 v64, v93, v64
	v_add_f32_e32 v64, v100, v64
	v_pk_mul_f32 v[96:97], v[84:85], v[84:85]
	v_add_f32_e32 v64, v101, v64
	v_add_f32_e32 v64, v96, v64
	v_add_f32_e32 v64, v97, v64
	ds_bpermute_b32 v65, v150, v64
	v_cvt_pk_bf16_f32 v66, v76, v77
	v_cvt_pk_bf16_f32 v67, v78, v79
	v_cvt_pk_bf16_f32 v68, v72, v73
	v_cvt_pk_bf16_f32 v69, v74, v75
	s_waitcnt lgkmcnt(0)
	v_add_f32_e32 v64, v64, v65
	ds_bpermute_b32 v65, v149, v64
	v_cvt_pk_bf16_f32 v70, v70, v71
	v_cvt_pk_bf16_f32 v71, v82, v83
	v_cvt_pk_bf16_f32 v72, v86, v87
	v_cvt_pk_bf16_f32 v73, v84, v85
	s_nop 1
	v_permlane16_swap_b32_e32 v66, v70
	v_permlane16_swap_b32_e32 v67, v71
	v_permlane16_swap_b32_e32 v68, v72
	v_permlane16_swap_b32_e32 v69, v73
	v_permlane32_swap_b32_e32 v66, v70
	v_permlane32_swap_b32_e32 v67, v71
	v_permlane32_swap_b32_e32 v68, v72
	v_permlane32_swap_b32_e32 v69, v73
	v_lshl_add_u64 v[238:239], v[98:99], 0, v[236:237]
	global_store_dwordx4 v[238:239], v[66:69], off
	global_store_dwordx4 v[238:239], v[70:73], off offset:64
	s_and_saveexec_b64 s[4:5], s[6:7]
	s_cbranch_execz .LBB0_1381
	v_lshlrev_b64 v[66:67], 6, v[80:81]
	v_lshl_add_u64 v[66:67], s[14:15], 0, v[66:67]
	v_lshl_add_u64 v[66:67], s[30:31], 2, v[66:67]
	s_lshl_b32 s8, s46, 2
	v_lshl_add_u64 v[66:67], v[66:67], 0, s[8:9]
	s_waitcnt lgkmcnt(0)
	v_add_f32_e32 v64, v64, v65
	global_store_dword v[66:67], v64, off
.LBB0_1381:
	s_or_b64 exec, exec, s[4:5]
	v_add_u32_e32 v64, 0x80, v140
	s_waitcnt lgkmcnt(0)
	v_ashrrev_i32_e32 v65, 31, v64
	v_readlane_b32 s60, v240, 5
	v_lshlrev_b64 v[66:67], 12, v[64:65]
	v_readlane_b32 s61, v240, 6
	v_lshlrev_b64 v[82:83], 11, v[64:65]
	v_lshl_add_u64 v[82:83], s[12:13], 0, v[82:83]
	v_lshl_add_u64 v[66:67], s[60:61], 0, v[66:67]
	v_lshl_add_u64 v[78:79], v[138:139], 2, v[66:67]
	v_lshl_add_u64 v[234:235], v[78:79], 0, v[232:233]
	global_load_dwordx4 v[66:69], v[234:235], off
	global_load_dwordx4 v[70:73], v[234:235], off offset:64
	global_load_dwordx4 v[74:77], v[234:235], off offset:128
	s_nop 0
	global_load_dwordx4 v[78:81], v[234:235], off offset:192
	v_lshl_add_u64 v[82:83], v[138:139], 1, v[82:83]
	v_readlane_b32 s62, v240, 7
	v_readlane_b32 s63, v240, 8
	s_waitcnt vmcnt(0)
	v_permlane16_swap_b32_e32 v66, v70
	v_permlane16_swap_b32_e32 v67, v71
	v_permlane16_swap_b32_e32 v68, v72
	v_permlane16_swap_b32_e32 v69, v73
	v_permlane16_swap_b32_e32 v74, v78
	v_permlane16_swap_b32_e32 v75, v79
	v_permlane16_swap_b32_e32 v76, v80
	v_permlane16_swap_b32_e32 v77, v81
	v_permlane32_swap_b32_e32 v66, v74
	v_permlane32_swap_b32_e32 v67, v75
	v_permlane32_swap_b32_e32 v68, v76
	v_permlane32_swap_b32_e32 v69, v77
	v_permlane32_swap_b32_e32 v70, v78
	v_permlane32_swap_b32_e32 v71, v79
	v_permlane32_swap_b32_e32 v72, v80
	v_permlane32_swap_b32_e32 v73, v81
	v_pk_add_f32 v[60:61], v[60:61], v[66:67]
	v_pk_add_f32 v[62:63], v[62:63], v[68:69]
	s_waitcnt vmcnt(1)
	v_pk_add_f32 v[66:67], v[54:55], v[76:77]
	v_pk_add_f32 v[54:55], v[52:53], v[74:75]
	v_pk_mul_f32 v[52:53], v[60:61], v[60:61]
	v_pk_add_f32 v[56:57], v[56:57], v[70:71]
	s_waitcnt vmcnt(0)
	v_pk_add_f32 v[68:69], v[50:51], v[80:81]
	v_pk_add_f32 v[70:71], v[48:49], v[78:79]
	v_pk_mul_f32 v[48:49], v[62:63], v[62:63]
	v_add_f32_e32 v51, v52, v53
	v_add_f32_e32 v48, v48, v51
	v_pk_mul_f32 v[74:75], v[56:57], v[56:57]
	v_add_f32_e32 v48, v49, v48
	v_pk_add_f32 v[58:59], v[58:59], v[72:73]
	v_add_f32_e32 v48, v74, v48
	v_pk_mul_f32 v[72:73], v[58:59], v[58:59]
	v_add_f32_e32 v48, v75, v48
	v_add_f32_e32 v48, v72, v48
	v_pk_mul_f32 v[78:79], v[54:55], v[54:55]
	v_add_f32_e32 v48, v73, v48
	v_add_f32_e32 v48, v78, v48
	v_pk_mul_f32 v[76:77], v[66:67], v[66:67]
	v_add_f32_e32 v48, v79, v48
	v_add_f32_e32 v48, v76, v48
	v_pk_mul_f32 v[84:85], v[70:71], v[70:71]
	v_add_f32_e32 v48, v77, v48
	v_add_f32_e32 v48, v84, v48
	v_pk_mul_f32 v[80:81], v[68:69], v[68:69]
	v_add_f32_e32 v48, v85, v48
	v_add_f32_e32 v48, v80, v48
	v_add_f32_e32 v48, v81, v48
	ds_bpermute_b32 v49, v150, v48
	v_cvt_pk_bf16_f32 v50, v60, v61
	v_cvt_pk_bf16_f32 v51, v62, v63
	v_cvt_pk_bf16_f32 v52, v56, v57
	v_cvt_pk_bf16_f32 v53, v58, v59
	s_waitcnt lgkmcnt(0)
	v_add_f32_e32 v48, v48, v49
	ds_bpermute_b32 v49, v149, v48
	v_cvt_pk_bf16_f32 v54, v54, v55
	v_cvt_pk_bf16_f32 v55, v66, v67
	v_cvt_pk_bf16_f32 v56, v70, v71
	v_cvt_pk_bf16_f32 v57, v68, v69
	s_nop 1
	v_permlane16_swap_b32_e32 v50, v54
	v_permlane16_swap_b32_e32 v51, v55
	v_permlane16_swap_b32_e32 v52, v56
	v_permlane16_swap_b32_e32 v53, v57
	v_permlane32_swap_b32_e32 v50, v54
	v_permlane32_swap_b32_e32 v51, v55
	v_permlane32_swap_b32_e32 v52, v56
	v_permlane32_swap_b32_e32 v53, v57
	v_lshl_add_u64 v[238:239], v[82:83], 0, v[236:237]
	global_store_dwordx4 v[238:239], v[50:53], off
	global_store_dwordx4 v[238:239], v[54:57], off offset:64
	s_and_saveexec_b64 s[4:5], s[6:7]
	s_cbranch_execz .LBB0_1383
	v_lshlrev_b64 v[50:51], 6, v[64:65]
	v_lshl_add_u64 v[50:51], s[14:15], 0, v[50:51]
	v_lshl_add_u64 v[50:51], s[30:31], 2, v[50:51]
	s_lshl_b32 s8, s46, 2
	v_lshl_add_u64 v[50:51], v[50:51], 0, s[8:9]
	s_waitcnt lgkmcnt(0)
	v_add_f32_e32 v48, v48, v49
	global_store_dword v[50:51], v48, off
.LBB0_1383:
	s_or_b64 exec, exec, s[4:5]
	v_add_u32_e32 v48, 0x90, v140
	s_waitcnt lgkmcnt(0)
	v_ashrrev_i32_e32 v49, 31, v48
	v_readlane_b32 s60, v240, 5
	v_lshlrev_b64 v[50:51], 12, v[48:49]
	v_readlane_b32 s61, v240, 6
	v_lshlrev_b64 v[66:67], 11, v[48:49]
	v_lshl_add_u64 v[66:67], s[12:13], 0, v[66:67]
	v_lshl_add_u64 v[50:51], s[60:61], 0, v[50:51]
	v_lshl_add_u64 v[62:63], v[138:139], 2, v[50:51]
	v_lshl_add_u64 v[234:235], v[62:63], 0, v[232:233]
	global_load_dwordx4 v[50:53], v[234:235], off
	global_load_dwordx4 v[54:57], v[234:235], off offset:64
	global_load_dwordx4 v[58:61], v[234:235], off offset:128
	s_nop 0
	global_load_dwordx4 v[62:65], v[234:235], off offset:192
	v_lshl_add_u64 v[66:67], v[138:139], 1, v[66:67]
	v_readlane_b32 s62, v240, 7
	v_readlane_b32 s63, v240, 8
	s_waitcnt vmcnt(0)
	v_permlane16_swap_b32_e32 v50, v54
	v_permlane16_swap_b32_e32 v51, v55
	v_permlane16_swap_b32_e32 v52, v56
	v_permlane16_swap_b32_e32 v53, v57
	v_permlane16_swap_b32_e32 v58, v62
	v_permlane16_swap_b32_e32 v59, v63
	v_permlane16_swap_b32_e32 v60, v64
	v_permlane16_swap_b32_e32 v61, v65
	v_permlane32_swap_b32_e32 v50, v58
	v_permlane32_swap_b32_e32 v51, v59
	v_permlane32_swap_b32_e32 v52, v60
	v_permlane32_swap_b32_e32 v53, v61
	v_permlane32_swap_b32_e32 v54, v62
	v_permlane32_swap_b32_e32 v55, v63
	v_permlane32_swap_b32_e32 v56, v64
	v_permlane32_swap_b32_e32 v57, v65
	v_pk_add_f32 v[44:45], v[44:45], v[50:51]
	v_pk_add_f32 v[46:47], v[46:47], v[52:53]
	s_waitcnt vmcnt(1)
	v_pk_add_f32 v[50:51], v[38:39], v[60:61]
	v_pk_add_f32 v[38:39], v[36:37], v[58:59]
	v_pk_mul_f32 v[36:37], v[44:45], v[44:45]
	v_pk_add_f32 v[40:41], v[40:41], v[54:55]
	s_waitcnt vmcnt(0)
	v_pk_add_f32 v[52:53], v[34:35], v[64:65]
	v_pk_add_f32 v[54:55], v[32:33], v[62:63]
	v_pk_mul_f32 v[32:33], v[46:47], v[46:47]
	v_add_f32_e32 v35, v36, v37
	v_add_f32_e32 v32, v32, v35
	v_pk_mul_f32 v[58:59], v[40:41], v[40:41]
	v_add_f32_e32 v32, v33, v32
	v_pk_add_f32 v[42:43], v[42:43], v[56:57]
	v_add_f32_e32 v32, v58, v32
	v_pk_mul_f32 v[56:57], v[42:43], v[42:43]
	v_add_f32_e32 v32, v59, v32
	v_add_f32_e32 v32, v56, v32
	v_pk_mul_f32 v[62:63], v[38:39], v[38:39]
	v_add_f32_e32 v32, v57, v32
	v_add_f32_e32 v32, v62, v32
	v_pk_mul_f32 v[60:61], v[50:51], v[50:51]
	v_add_f32_e32 v32, v63, v32
	v_add_f32_e32 v32, v60, v32
	v_pk_mul_f32 v[68:69], v[54:55], v[54:55]
	v_add_f32_e32 v32, v61, v32
	v_add_f32_e32 v32, v68, v32
	v_pk_mul_f32 v[64:65], v[52:53], v[52:53]
	v_add_f32_e32 v32, v69, v32
	v_add_f32_e32 v32, v64, v32
	v_add_f32_e32 v32, v65, v32
	ds_bpermute_b32 v33, v150, v32
	v_cvt_pk_bf16_f32 v34, v44, v45
	v_cvt_pk_bf16_f32 v35, v46, v47
	v_cvt_pk_bf16_f32 v36, v40, v41
	v_cvt_pk_bf16_f32 v37, v42, v43
	s_waitcnt lgkmcnt(0)
	v_add_f32_e32 v32, v32, v33
	ds_bpermute_b32 v33, v149, v32
	v_cvt_pk_bf16_f32 v38, v38, v39
	v_cvt_pk_bf16_f32 v39, v50, v51
	v_cvt_pk_bf16_f32 v40, v54, v55
	v_cvt_pk_bf16_f32 v41, v52, v53
	s_nop 1
	v_permlane16_swap_b32_e32 v34, v38
	v_permlane16_swap_b32_e32 v35, v39
	v_permlane16_swap_b32_e32 v36, v40
	v_permlane16_swap_b32_e32 v37, v41
	v_permlane32_swap_b32_e32 v34, v38
	v_permlane32_swap_b32_e32 v35, v39
	v_permlane32_swap_b32_e32 v36, v40
	v_permlane32_swap_b32_e32 v37, v41
	v_lshl_add_u64 v[238:239], v[66:67], 0, v[236:237]
	global_store_dwordx4 v[238:239], v[34:37], off
	global_store_dwordx4 v[238:239], v[38:41], off offset:64
	s_and_saveexec_b64 s[4:5], s[6:7]
	s_cbranch_execz .LBB0_1385
	v_lshlrev_b64 v[34:35], 6, v[48:49]
	v_lshl_add_u64 v[34:35], s[14:15], 0, v[34:35]
	v_lshl_add_u64 v[34:35], s[30:31], 2, v[34:35]
	s_lshl_b32 s8, s46, 2
	v_lshl_add_u64 v[34:35], v[34:35], 0, s[8:9]
	s_waitcnt lgkmcnt(0)
	v_add_f32_e32 v32, v32, v33
	global_store_dword v[34:35], v32, off
.LBB0_1385:
	s_or_b64 exec, exec, s[4:5]
	v_add_u32_e32 v32, 0xa0, v140
	s_waitcnt lgkmcnt(0)
	v_ashrrev_i32_e32 v33, 31, v32
	v_readlane_b32 s60, v240, 5
	v_lshlrev_b64 v[34:35], 12, v[32:33]
	v_readlane_b32 s61, v240, 6
	v_lshlrev_b64 v[50:51], 11, v[32:33]
	v_lshl_add_u64 v[50:51], s[12:13], 0, v[50:51]
	v_lshl_add_u64 v[34:35], s[60:61], 0, v[34:35]
	v_lshl_add_u64 v[46:47], v[138:139], 2, v[34:35]
	v_lshl_add_u64 v[234:235], v[46:47], 0, v[232:233]
	global_load_dwordx4 v[34:37], v[234:235], off
	global_load_dwordx4 v[38:41], v[234:235], off offset:64
	global_load_dwordx4 v[42:45], v[234:235], off offset:128
	s_nop 0
	global_load_dwordx4 v[46:49], v[234:235], off offset:192
	v_lshl_add_u64 v[50:51], v[138:139], 1, v[50:51]
	v_readlane_b32 s62, v240, 7
	v_readlane_b32 s63, v240, 8
	s_waitcnt vmcnt(0)
	v_permlane16_swap_b32_e32 v34, v38
	v_permlane16_swap_b32_e32 v35, v39
	v_permlane16_swap_b32_e32 v36, v40
	v_permlane16_swap_b32_e32 v37, v41
	v_permlane16_swap_b32_e32 v42, v46
	v_permlane16_swap_b32_e32 v43, v47
	v_permlane16_swap_b32_e32 v44, v48
	v_permlane16_swap_b32_e32 v45, v49
	v_permlane32_swap_b32_e32 v34, v42
	v_permlane32_swap_b32_e32 v35, v43
	v_permlane32_swap_b32_e32 v36, v44
	v_permlane32_swap_b32_e32 v37, v45
	v_permlane32_swap_b32_e32 v38, v46
	v_permlane32_swap_b32_e32 v39, v47
	v_permlane32_swap_b32_e32 v40, v48
	v_permlane32_swap_b32_e32 v41, v49
	v_pk_add_f32 v[28:29], v[28:29], v[34:35]
	v_pk_add_f32 v[30:31], v[30:31], v[36:37]
	s_waitcnt vmcnt(1)
	v_pk_add_f32 v[34:35], v[22:23], v[44:45]
	v_pk_add_f32 v[22:23], v[20:21], v[42:43]
	v_pk_mul_f32 v[20:21], v[28:29], v[28:29]
	v_pk_add_f32 v[24:25], v[24:25], v[38:39]
	s_waitcnt vmcnt(0)
	v_pk_add_f32 v[36:37], v[18:19], v[48:49]
	v_pk_add_f32 v[38:39], v[16:17], v[46:47]
	v_pk_mul_f32 v[16:17], v[30:31], v[30:31]
	v_add_f32_e32 v19, v20, v21
	v_add_f32_e32 v16, v16, v19
	v_pk_mul_f32 v[42:43], v[24:25], v[24:25]
	v_add_f32_e32 v16, v17, v16
	v_pk_add_f32 v[26:27], v[26:27], v[40:41]
	v_add_f32_e32 v16, v42, v16
	v_pk_mul_f32 v[40:41], v[26:27], v[26:27]
	v_add_f32_e32 v16, v43, v16
	v_add_f32_e32 v16, v40, v16
	v_pk_mul_f32 v[46:47], v[22:23], v[22:23]
	v_add_f32_e32 v16, v41, v16
	v_add_f32_e32 v16, v46, v16
	v_pk_mul_f32 v[44:45], v[34:35], v[34:35]
	v_add_f32_e32 v16, v47, v16
	v_add_f32_e32 v16, v44, v16
	v_pk_mul_f32 v[52:53], v[38:39], v[38:39]
	v_add_f32_e32 v16, v45, v16
	v_add_f32_e32 v16, v52, v16
	v_pk_mul_f32 v[48:49], v[36:37], v[36:37]
	v_add_f32_e32 v16, v53, v16
	v_add_f32_e32 v16, v48, v16
	v_add_f32_e32 v16, v49, v16
	ds_bpermute_b32 v17, v150, v16
	v_cvt_pk_bf16_f32 v18, v28, v29
	v_cvt_pk_bf16_f32 v19, v30, v31
	v_cvt_pk_bf16_f32 v20, v24, v25
	v_cvt_pk_bf16_f32 v21, v26, v27
	s_waitcnt lgkmcnt(0)
	v_add_f32_e32 v16, v16, v17
	ds_bpermute_b32 v17, v149, v16
	v_cvt_pk_bf16_f32 v22, v22, v23
	v_cvt_pk_bf16_f32 v23, v34, v35
	v_cvt_pk_bf16_f32 v24, v38, v39
	v_cvt_pk_bf16_f32 v25, v36, v37
	s_nop 1
	v_permlane16_swap_b32_e32 v18, v22
	v_permlane16_swap_b32_e32 v19, v23
	v_permlane16_swap_b32_e32 v20, v24
	v_permlane16_swap_b32_e32 v21, v25
	v_permlane32_swap_b32_e32 v18, v22
	v_permlane32_swap_b32_e32 v19, v23
	v_permlane32_swap_b32_e32 v20, v24
	v_permlane32_swap_b32_e32 v21, v25
	v_lshl_add_u64 v[238:239], v[50:51], 0, v[236:237]
	global_store_dwordx4 v[238:239], v[18:21], off
	global_store_dwordx4 v[238:239], v[22:25], off offset:64
	s_and_saveexec_b64 s[4:5], s[6:7]
	s_cbranch_execz .LBB0_1387
	v_lshlrev_b64 v[18:19], 6, v[32:33]
	v_lshl_add_u64 v[18:19], s[14:15], 0, v[18:19]
	v_lshl_add_u64 v[18:19], s[30:31], 2, v[18:19]
	s_lshl_b32 s8, s46, 2
	v_lshl_add_u64 v[18:19], v[18:19], 0, s[8:9]
	s_waitcnt lgkmcnt(0)
	v_add_f32_e32 v16, v16, v17
	global_store_dword v[18:19], v16, off
.LBB0_1387:
	s_or_b64 exec, exec, s[4:5]
	v_add_u32_e32 v16, 0xb0, v140
	s_waitcnt lgkmcnt(0)
	v_ashrrev_i32_e32 v17, 31, v16
	v_readlane_b32 s60, v240, 5
	v_lshlrev_b64 v[18:19], 12, v[16:17]
	v_readlane_b32 s61, v240, 6
	v_lshlrev_b64 v[34:35], 11, v[16:17]
	v_lshl_add_u64 v[34:35], s[12:13], 0, v[34:35]
	v_lshl_add_u64 v[18:19], s[60:61], 0, v[18:19]
	v_lshl_add_u64 v[30:31], v[138:139], 2, v[18:19]
	v_lshl_add_u64 v[234:235], v[30:31], 0, v[232:233]
	global_load_dwordx4 v[18:21], v[234:235], off
	global_load_dwordx4 v[22:25], v[234:235], off offset:64
	global_load_dwordx4 v[26:29], v[234:235], off offset:128
	s_nop 0
	global_load_dwordx4 v[30:33], v[234:235], off offset:192
	v_lshl_add_u64 v[34:35], v[138:139], 1, v[34:35]
	v_readlane_b32 s62, v240, 7
	v_readlane_b32 s63, v240, 8
	s_waitcnt vmcnt(0)
	v_permlane16_swap_b32_e32 v18, v22
	v_permlane16_swap_b32_e32 v19, v23
	v_permlane16_swap_b32_e32 v20, v24
	v_permlane16_swap_b32_e32 v21, v25
	v_permlane16_swap_b32_e32 v26, v30
	v_permlane16_swap_b32_e32 v27, v31
	v_permlane16_swap_b32_e32 v28, v32
	v_permlane16_swap_b32_e32 v29, v33
	v_permlane32_swap_b32_e32 v18, v26
	v_permlane32_swap_b32_e32 v19, v27
	v_permlane32_swap_b32_e32 v20, v28
	v_permlane32_swap_b32_e32 v21, v29
	v_permlane32_swap_b32_e32 v22, v30
	v_permlane32_swap_b32_e32 v23, v31
	v_permlane32_swap_b32_e32 v24, v32
	v_permlane32_swap_b32_e32 v25, v33
	v_pk_add_f32 v[12:13], v[12:13], v[18:19]
	v_pk_add_f32 v[14:15], v[14:15], v[20:21]
	s_waitcnt vmcnt(1)
	v_pk_add_f32 v[18:19], v[6:7], v[28:29]
	v_pk_add_f32 v[6:7], v[4:5], v[26:27]
	v_pk_mul_f32 v[4:5], v[12:13], v[12:13]
	v_pk_add_f32 v[8:9], v[8:9], v[22:23]
	s_waitcnt vmcnt(0)
	v_pk_add_f32 v[20:21], v[2:3], v[32:33]
	v_pk_add_f32 v[22:23], v[0:1], v[30:31]
	v_pk_mul_f32 v[0:1], v[14:15], v[14:15]
	v_add_f32_e32 v3, v4, v5
	v_add_f32_e32 v0, v0, v3
	v_pk_mul_f32 v[26:27], v[8:9], v[8:9]
	v_add_f32_e32 v0, v1, v0
	v_pk_add_f32 v[10:11], v[10:11], v[24:25]
	v_add_f32_e32 v0, v26, v0
	v_pk_mul_f32 v[24:25], v[10:11], v[10:11]
	v_add_f32_e32 v0, v27, v0
	v_add_f32_e32 v0, v24, v0
	v_pk_mul_f32 v[30:31], v[6:7], v[6:7]
	v_add_f32_e32 v0, v25, v0
	v_add_f32_e32 v0, v30, v0
	v_pk_mul_f32 v[28:29], v[18:19], v[18:19]
	v_add_f32_e32 v0, v31, v0
	v_add_f32_e32 v0, v28, v0
	v_pk_mul_f32 v[36:37], v[22:23], v[22:23]
	v_add_f32_e32 v0, v29, v0
	v_add_f32_e32 v0, v36, v0
	v_pk_mul_f32 v[32:33], v[20:21], v[20:21]
	v_add_f32_e32 v0, v37, v0
	v_add_f32_e32 v0, v32, v0
	v_add_f32_e32 v0, v33, v0
	ds_bpermute_b32 v1, v150, v0
	v_cvt_pk_bf16_f32 v2, v12, v13
	v_cvt_pk_bf16_f32 v3, v14, v15
	v_cvt_pk_bf16_f32 v4, v8, v9
	v_cvt_pk_bf16_f32 v5, v10, v11
	s_waitcnt lgkmcnt(0)
	v_add_f32_e32 v0, v0, v1
	ds_bpermute_b32 v1, v149, v0
	v_cvt_pk_bf16_f32 v6, v6, v7
	v_cvt_pk_bf16_f32 v7, v18, v19
	v_cvt_pk_bf16_f32 v8, v22, v23
	v_cvt_pk_bf16_f32 v9, v20, v21
	s_nop 1
	v_permlane16_swap_b32_e32 v2, v6
	v_permlane16_swap_b32_e32 v3, v7
	v_permlane16_swap_b32_e32 v4, v8
	v_permlane16_swap_b32_e32 v5, v9
	v_permlane32_swap_b32_e32 v2, v6
	v_permlane32_swap_b32_e32 v3, v7
	v_permlane32_swap_b32_e32 v4, v8
	v_permlane32_swap_b32_e32 v5, v9
	v_lshl_add_u64 v[238:239], v[34:35], 0, v[236:237]
	global_store_dwordx4 v[238:239], v[2:5], off
	global_store_dwordx4 v[238:239], v[6:9], off offset:64
	s_and_saveexec_b64 s[4:5], s[6:7]
	s_cbranch_execz .LBB0_1389
	v_lshlrev_b64 v[2:3], 6, v[16:17]
	v_lshl_add_u64 v[2:3], s[14:15], 0, v[2:3]
	v_lshl_add_u64 v[2:3], s[30:31], 2, v[2:3]
	s_lshl_b32 s8, s46, 2
	v_lshl_add_u64 v[2:3], v[2:3], 0, s[8:9]
	s_waitcnt lgkmcnt(0)
	v_add_f32_e32 v0, v0, v1
	global_store_dword v[2:3], v0, off

.LBB0_1555:
	v_and_b32_e32 v236, 48, v144
	v_sub_u32_e32 v236, 0, v236
	v_ashrrev_i32_e32 v237, 31, v236
	v_lshl_add_u32 v140, s55, 8, v142
	v_ashrrev_i32_e32 v141, 31, v140
	v_lshl_or_b32 v138, s8, 8, v144
	v_lshlrev_b64 v[150:151], 11, v[140:141]
	v_ashrrev_i32_e32 v139, 31, v138
	v_lshl_add_u64 v[150:151], s[12:13], 0, v[150:151]
	v_lshl_add_u64 v[160:161], v[138:139], 1, v[150:151]
	v_lshl_add_u64 v[234:235], v[160:161], 0, v[236:237]
	global_load_dwordx4 v[152:155], v[234:235], off
	global_load_dwordx4 v[156:159], v[234:235], off offset:64
	v_and_b32_e32 v150, 64, v148
	v_xor_b32_e32 v149, 16, v148
	v_add_u32_e32 v150, 64, v150
	v_cmp_lt_i32_e32 vcc, v149, v150
	v_xor_b32_e32 v151, 32, v148
	s_lshl_b32 s26, s8, 2
	v_cndmask_b32_e32 v149, v148, v149, vcc
	v_cmp_lt_i32_e32 vcc, v151, v150
	v_lshlrev_b32_e32 v150, 2, v149
	s_ashr_i32 s27, s26, 31
	v_cndmask_b32_e32 v151, v148, v151, vcc
	v_lshlrev_b32_e32 v149, 2, v151
	s_waitcnt vmcnt(0)
	v_permlane32_swap_b32_e32 v152, v156
	v_permlane32_swap_b32_e32 v153, v157
	v_permlane32_swap_b32_e32 v154, v158
	v_permlane32_swap_b32_e32 v155, v159
	v_permlane16_swap_b32_e32 v152, v156
	v_permlane16_swap_b32_e32 v153, v157
	v_permlane16_swap_b32_e32 v154, v158
	v_permlane16_swap_b32_e32 v155, v159
	v_lshlrev_b32_e32 v162, 16, v152
	v_and_b32_e32 v163, 0xffff0000, v152
	v_lshlrev_b32_e32 v152, 16, v153
	v_and_b32_e32 v153, 0xffff0000, v153
	v_lshlrev_b32_e32 v164, 16, v154
	v_and_b32_e32 v165, 0xffff0000, v154
	v_lshlrev_b32_e32 v154, 16, v155
	v_and_b32_e32 v155, 0xffff0000, v155
	v_lshlrev_b32_e32 v166, 16, v156
	v_and_b32_e32 v167, 0xffff0000, v156
	v_lshlrev_b32_e32 v156, 16, v157
	v_and_b32_e32 v157, 0xffff0000, v157
	v_lshlrev_b32_e32 v168, 16, v158
	v_and_b32_e32 v169, 0xffff0000, v158
	v_pk_add_f32 v[120:121], v[120:121], v[162:163]
	v_pk_add_f32 v[122:123], v[122:123], v[152:153]
	v_pk_add_f32 v[126:127], v[126:127], v[154:155]
	v_pk_add_f32 v[154:155], v[118:119], v[156:157]
	v_pk_add_f32 v[156:157], v[112:113], v[168:169]
	v_pk_mul_f32 v[112:113], v[120:121], v[120:121]
	v_pk_add_f32 v[152:153], v[116:117], v[166:167]
	v_pk_mul_f32 v[116:117], v[122:123], v[122:123]
	v_add_f32_e32 v112, v112, v113
	v_pk_add_f32 v[124:125], v[124:125], v[164:165]
	v_add_f32_e32 v112, v116, v112
	v_pk_mul_f32 v[118:119], v[124:125], v[124:125]
	v_add_f32_e32 v112, v117, v112
	v_add_f32_e32 v112, v118, v112
	v_pk_mul_f32 v[162:163], v[126:127], v[126:127]
	v_add_f32_e32 v112, v119, v112
	v_add_f32_e32 v112, v162, v112
	v_pk_mul_f32 v[164:165], v[152:153], v[152:153]
	v_add_f32_e32 v112, v163, v112
	v_add_f32_e32 v112, v164, v112
	v_pk_mul_f32 v[166:167], v[154:155], v[154:155]
	v_add_f32_e32 v112, v165, v112
	v_add_f32_e32 v112, v166, v112
	v_lshlrev_b32_e32 v158, 16, v159
	v_and_b32_e32 v159, 0xffff0000, v159
	v_pk_mul_f32 v[168:169], v[156:157], v[156:157]
	v_add_f32_e32 v112, v167, v112
	v_pk_add_f32 v[158:159], v[114:115], v[158:159]
	v_add_f32_e32 v112, v168, v112
	v_pk_mul_f32 v[170:171], v[158:159], v[158:159]
	v_add_f32_e32 v112, v169, v112
	v_add_f32_e32 v112, v170, v112
	v_add_f32_e32 v112, v171, v112
	ds_bpermute_b32 v113, v150, v112
	v_cvt_pk_bf16_f32 v114, v120, v121
	v_cvt_pk_bf16_f32 v115, v122, v123
	v_cvt_pk_bf16_f32 v116, v124, v125
	v_cvt_pk_bf16_f32 v117, v126, v127
	s_waitcnt lgkmcnt(0)
	v_add_f32_e32 v112, v112, v113
	ds_bpermute_b32 v113, v149, v112
	v_cvt_pk_bf16_f32 v118, v152, v153
	v_cvt_pk_bf16_f32 v119, v154, v155
	v_cvt_pk_bf16_f32 v120, v156, v157
	v_cvt_pk_bf16_f32 v121, v158, v159
	s_nop 1
	v_permlane16_swap_b32_e32 v114, v118
	v_permlane16_swap_b32_e32 v115, v119
	v_permlane16_swap_b32_e32 v116, v120
	v_permlane16_swap_b32_e32 v117, v121
	v_permlane32_swap_b32_e32 v114, v118
	v_permlane32_swap_b32_e32 v115, v119
	v_permlane32_swap_b32_e32 v116, v120
	v_permlane32_swap_b32_e32 v117, v121
	v_lshl_add_u64 v[238:239], v[160:161], 0, v[236:237]
	global_store_dwordx4 v[238:239], v[114:117], off
	global_store_dwordx4 v[238:239], v[118:121], off offset:64
	s_and_saveexec_b64 s[4:5], s[6:7]
	s_cbranch_execz .LBB0_1557
	s_waitcnt lgkmcnt(0)
	v_add_f32_e32 v114, v112, v113
	v_lshlrev_b64 v[112:113], 6, v[140:141]
	v_lshl_add_u64 v[112:113], s[14:15], 0, v[112:113]
	v_lshl_add_u64 v[112:113], s[26:27], 2, v[112:113]
	s_lshl_b32 s8, s40, 2
	v_lshl_add_u64 v[112:113], v[112:113], 0, s[8:9]
	global_store_dword v[112:113], v114, off
.LBB0_1557:
	s_or_b64 exec, exec, s[4:5]
	v_or_b32_e32 v112, 16, v140
	s_waitcnt lgkmcnt(0)
	v_ashrrev_i32_e32 v113, 31, v112
	v_lshlrev_b64 v[114:115], 11, v[112:113]
	v_lshl_add_u64 v[114:115], s[12:13], 0, v[114:115]
	v_lshl_add_u64 v[122:123], v[138:139], 1, v[114:115]
	v_lshl_add_u64 v[234:235], v[122:123], 0, v[236:237]
	global_load_dwordx4 v[114:117], v[234:235], off
	global_load_dwordx4 v[118:121], v[234:235], off offset:64
	s_waitcnt vmcnt(0)
	v_permlane32_swap_b32_e32 v114, v118
	v_permlane32_swap_b32_e32 v115, v119
	v_permlane32_swap_b32_e32 v116, v120
	v_permlane32_swap_b32_e32 v117, v121
	v_permlane16_swap_b32_e32 v114, v118
	v_permlane16_swap_b32_e32 v115, v119
	v_permlane16_swap_b32_e32 v116, v120
	v_permlane16_swap_b32_e32 v117, v121
	v_lshlrev_b32_e32 v124, 16, v114
	v_and_b32_e32 v125, 0xffff0000, v114
	v_lshlrev_b32_e32 v114, 16, v115
	v_and_b32_e32 v115, 0xffff0000, v115
	v_lshlrev_b32_e32 v126, 16, v116
	v_and_b32_e32 v127, 0xffff0000, v116
	v_lshlrev_b32_e32 v116, 16, v117
	v_and_b32_e32 v117, 0xffff0000, v117
	s_waitcnt vmcnt(0)
	v_lshlrev_b32_e32 v152, 16, v118
	v_and_b32_e32 v153, 0xffff0000, v118
	v_lshlrev_b32_e32 v118, 16, v119
	v_and_b32_e32 v119, 0xffff0000, v119
	v_lshlrev_b32_e32 v154, 16, v120
	v_and_b32_e32 v155, 0xffff0000, v120
	v_pk_add_f32 v[108:109], v[108:109], v[124:125]
	v_pk_add_f32 v[110:111], v[110:111], v[114:115]
	v_pk_add_f32 v[106:107], v[106:107], v[116:117]
	v_pk_add_f32 v[116:117], v[102:103], v[118:119]
	v_pk_add_f32 v[118:119], v[96:97], v[154:155]
	v_pk_mul_f32 v[96:97], v[108:109], v[108:109]
	v_pk_add_f32 v[114:115], v[100:101], v[152:153]
	v_pk_mul_f32 v[100:101], v[110:111], v[110:111]
	v_add_f32_e32 v96, v96, v97
	v_pk_add_f32 v[104:105], v[104:105], v[126:127]
	v_add_f32_e32 v96, v100, v96
	v_pk_mul_f32 v[102:103], v[104:105], v[104:105]
	v_add_f32_e32 v96, v101, v96
	v_add_f32_e32 v96, v102, v96
	v_pk_mul_f32 v[124:125], v[106:107], v[106:107]
	v_add_f32_e32 v96, v103, v96
	v_add_f32_e32 v96, v124, v96
	v_pk_mul_f32 v[126:127], v[114:115], v[114:115]
	v_add_f32_e32 v96, v125, v96
	v_add_f32_e32 v96, v126, v96
	v_pk_mul_f32 v[152:153], v[116:117], v[116:117]
	v_add_f32_e32 v96, v127, v96
	v_add_f32_e32 v96, v152, v96
	v_lshlrev_b32_e32 v120, 16, v121
	v_and_b32_e32 v121, 0xffff0000, v121
	v_pk_mul_f32 v[154:155], v[118:119], v[118:119]
	v_add_f32_e32 v96, v153, v96
	v_pk_add_f32 v[120:121], v[98:99], v[120:121]
	v_add_f32_e32 v96, v154, v96
	v_pk_mul_f32 v[156:157], v[120:121], v[120:121]
	v_add_f32_e32 v96, v155, v96
	v_add_f32_e32 v96, v156, v96
	v_add_f32_e32 v96, v157, v96
	ds_bpermute_b32 v97, v150, v96
	v_cvt_pk_bf16_f32 v98, v108, v109
	v_cvt_pk_bf16_f32 v99, v110, v111
	v_cvt_pk_bf16_f32 v100, v104, v105
	v_cvt_pk_bf16_f32 v101, v106, v107
	s_waitcnt lgkmcnt(0)
	v_add_f32_e32 v96, v96, v97
	ds_bpermute_b32 v97, v149, v96
	v_cvt_pk_bf16_f32 v102, v114, v115
	v_cvt_pk_bf16_f32 v103, v116, v117
	v_cvt_pk_bf16_f32 v104, v118, v119
	v_cvt_pk_bf16_f32 v105, v120, v121
	s_nop 1
	v_permlane16_swap_b32_e32 v98, v102
	v_permlane16_swap_b32_e32 v99, v103
	v_permlane16_swap_b32_e32 v100, v104
	v_permlane16_swap_b32_e32 v101, v105
	v_permlane32_swap_b32_e32 v98, v102
	v_permlane32_swap_b32_e32 v99, v103
	v_permlane32_swap_b32_e32 v100, v104
	v_permlane32_swap_b32_e32 v101, v105
	v_lshl_add_u64 v[238:239], v[122:123], 0, v[236:237]
	global_store_dwordx4 v[238:239], v[98:101], off
	global_store_dwordx4 v[238:239], v[102:105], off offset:64
	s_and_saveexec_b64 s[4:5], s[6:7]
	s_cbranch_execz .LBB0_1559
	s_waitcnt lgkmcnt(0)
	v_add_f32_e32 v98, v96, v97
	v_lshlrev_b64 v[96:97], 6, v[112:113]
	v_lshl_add_u64 v[96:97], s[14:15], 0, v[96:97]
	v_lshl_add_u64 v[96:97], s[26:27], 2, v[96:97]
	s_lshl_b32 s8, s40, 2
	v_lshl_add_u64 v[96:97], v[96:97], 0, s[8:9]
	global_store_dword v[96:97], v98, off
.LBB0_1559:
	s_or_b64 exec, exec, s[4:5]
	v_or_b32_e32 v96, 32, v140
	s_waitcnt lgkmcnt(0)
	v_ashrrev_i32_e32 v97, 31, v96
	v_lshlrev_b64 v[98:99], 11, v[96:97]
	v_lshl_add_u64 v[98:99], s[12:13], 0, v[98:99]
	v_lshl_add_u64 v[106:107], v[138:139], 1, v[98:99]
	v_lshl_add_u64 v[234:235], v[106:107], 0, v[236:237]
	global_load_dwordx4 v[98:101], v[234:235], off
	global_load_dwordx4 v[102:105], v[234:235], off offset:64
	s_waitcnt vmcnt(0)
	v_permlane32_swap_b32_e32 v98, v102
	v_permlane32_swap_b32_e32 v99, v103
	v_permlane32_swap_b32_e32 v100, v104
	v_permlane32_swap_b32_e32 v101, v105
	v_permlane16_swap_b32_e32 v98, v102
	v_permlane16_swap_b32_e32 v99, v103
	v_permlane16_swap_b32_e32 v100, v104
	v_permlane16_swap_b32_e32 v101, v105
	v_lshlrev_b32_e32 v108, 16, v98
	v_and_b32_e32 v109, 0xffff0000, v98
	v_lshlrev_b32_e32 v98, 16, v99
	v_and_b32_e32 v99, 0xffff0000, v99
	v_lshlrev_b32_e32 v110, 16, v100
	v_and_b32_e32 v111, 0xffff0000, v100
	v_lshlrev_b32_e32 v100, 16, v101
	v_and_b32_e32 v101, 0xffff0000, v101
	s_waitcnt vmcnt(0)
	v_lshlrev_b32_e32 v112, 16, v102
	v_and_b32_e32 v113, 0xffff0000, v102
	v_lshlrev_b32_e32 v102, 16, v103
	v_and_b32_e32 v103, 0xffff0000, v103
	v_lshlrev_b32_e32 v114, 16, v104
	v_and_b32_e32 v115, 0xffff0000, v104
	v_pk_add_f32 v[92:93], v[92:93], v[108:109]
	v_pk_add_f32 v[94:95], v[94:95], v[98:99]
	v_pk_add_f32 v[90:91], v[90:91], v[100:101]
	v_pk_add_f32 v[100:101], v[86:87], v[102:103]
	v_pk_add_f32 v[102:103], v[80:81], v[114:115]
	v_pk_mul_f32 v[80:81], v[92:93], v[92:93]
	v_pk_add_f32 v[98:99], v[84:85], v[112:113]
	v_pk_mul_f32 v[84:85], v[94:95], v[94:95]
	v_add_f32_e32 v80, v80, v81
	v_pk_add_f32 v[88:89], v[88:89], v[110:111]
	v_add_f32_e32 v80, v84, v80
	v_pk_mul_f32 v[86:87], v[88:89], v[88:89]
	v_add_f32_e32 v80, v85, v80
	v_add_f32_e32 v80, v86, v80
	v_pk_mul_f32 v[108:109], v[90:91], v[90:91]
	v_add_f32_e32 v80, v87, v80
	v_add_f32_e32 v80, v108, v80
	v_pk_mul_f32 v[110:111], v[98:99], v[98:99]
	v_add_f32_e32 v80, v109, v80
	v_add_f32_e32 v80, v110, v80
	v_pk_mul_f32 v[112:113], v[100:101], v[100:101]
	v_add_f32_e32 v80, v111, v80
	v_add_f32_e32 v80, v112, v80
	v_lshlrev_b32_e32 v104, 16, v105
	v_and_b32_e32 v105, 0xffff0000, v105
	v_pk_mul_f32 v[114:115], v[102:103], v[102:103]
	v_add_f32_e32 v80, v113, v80
	v_pk_add_f32 v[104:105], v[82:83], v[104:105]
	v_add_f32_e32 v80, v114, v80
	v_pk_mul_f32 v[116:117], v[104:105], v[104:105]
	v_add_f32_e32 v80, v115, v80
	v_add_f32_e32 v80, v116, v80
	v_add_f32_e32 v80, v117, v80
	ds_bpermute_b32 v81, v150, v80
	v_cvt_pk_bf16_f32 v82, v92, v93
	v_cvt_pk_bf16_f32 v83, v94, v95
	v_cvt_pk_bf16_f32 v84, v88, v89
	v_cvt_pk_bf16_f32 v85, v90, v91
	s_waitcnt lgkmcnt(0)
	v_add_f32_e32 v80, v80, v81
	ds_bpermute_b32 v81, v149, v80
	v_cvt_pk_bf16_f32 v86, v98, v99
	v_cvt_pk_bf16_f32 v87, v100, v101
	v_cvt_pk_bf16_f32 v88, v102, v103
	v_cvt_pk_bf16_f32 v89, v104, v105
	s_nop 1
	v_permlane16_swap_b32_e32 v82, v86
	v_permlane16_swap_b32_e32 v83, v87
	v_permlane16_swap_b32_e32 v84, v88
	v_permlane16_swap_b32_e32 v85, v89
	v_permlane32_swap_b32_e32 v82, v86
	v_permlane32_swap_b32_e32 v83, v87
	v_permlane32_swap_b32_e32 v84, v88
	v_permlane32_swap_b32_e32 v85, v89
	v_lshl_add_u64 v[238:239], v[106:107], 0, v[236:237]
	global_store_dwordx4 v[238:239], v[82:85], off
	global_store_dwordx4 v[238:239], v[86:89], off offset:64
	s_and_saveexec_b64 s[4:5], s[6:7]
	s_cbranch_execz .LBB0_1561
	s_waitcnt lgkmcnt(0)
	v_add_f32_e32 v82, v80, v81
	v_lshlrev_b64 v[80:81], 6, v[96:97]
	v_lshl_add_u64 v[80:81], s[14:15], 0, v[80:81]
	v_lshl_add_u64 v[80:81], s[26:27], 2, v[80:81]
	s_lshl_b32 s8, s40, 2
	v_lshl_add_u64 v[80:81], v[80:81], 0, s[8:9]
	global_store_dword v[80:81], v82, off
.LBB0_1561:
	s_or_b64 exec, exec, s[4:5]
	v_or_b32_e32 v80, 48, v140
	s_waitcnt lgkmcnt(0)
	v_ashrrev_i32_e32 v81, 31, v80
	v_lshlrev_b64 v[82:83], 11, v[80:81]
	v_lshl_add_u64 v[82:83], s[12:13], 0, v[82:83]
	v_lshl_add_u64 v[90:91], v[138:139], 1, v[82:83]
	v_lshl_add_u64 v[234:235], v[90:91], 0, v[236:237]
	global_load_dwordx4 v[82:85], v[234:235], off
	global_load_dwordx4 v[86:89], v[234:235], off offset:64
	s_waitcnt vmcnt(0)
	v_permlane32_swap_b32_e32 v82, v86
	v_permlane32_swap_b32_e32 v83, v87
	v_permlane32_swap_b32_e32 v84, v88
	v_permlane32_swap_b32_e32 v85, v89
	v_permlane16_swap_b32_e32 v82, v86
	v_permlane16_swap_b32_e32 v83, v87
	v_permlane16_swap_b32_e32 v84, v88
	v_permlane16_swap_b32_e32 v85, v89
	v_lshlrev_b32_e32 v92, 16, v82
	v_and_b32_e32 v93, 0xffff0000, v82
	v_lshlrev_b32_e32 v82, 16, v83
	v_and_b32_e32 v83, 0xffff0000, v83
	v_lshlrev_b32_e32 v94, 16, v84
	v_and_b32_e32 v95, 0xffff0000, v84
	v_lshlrev_b32_e32 v84, 16, v85
	v_and_b32_e32 v85, 0xffff0000, v85
	s_waitcnt vmcnt(0)
	v_lshlrev_b32_e32 v96, 16, v86
	v_and_b32_e32 v97, 0xffff0000, v86
	v_lshlrev_b32_e32 v86, 16, v87
	v_and_b32_e32 v87, 0xffff0000, v87
	v_lshlrev_b32_e32 v98, 16, v88
	v_and_b32_e32 v99, 0xffff0000, v88
	v_pk_add_f32 v[76:77], v[76:77], v[92:93]
	v_pk_add_f32 v[78:79], v[78:79], v[82:83]
	v_pk_add_f32 v[74:75], v[74:75], v[84:85]
	v_pk_add_f32 v[84:85], v[70:71], v[86:87]
	v_pk_add_f32 v[86:87], v[64:65], v[98:99]
	v_pk_mul_f32 v[64:65], v[76:77], v[76:77]
	v_pk_add_f32 v[82:83], v[68:69], v[96:97]
	v_pk_mul_f32 v[68:69], v[78:79], v[78:79]
	v_add_f32_e32 v64, v64, v65
	v_pk_add_f32 v[72:73], v[72:73], v[94:95]
	v_add_f32_e32 v64, v68, v64
	v_pk_mul_f32 v[70:71], v[72:73], v[72:73]
	v_add_f32_e32 v64, v69, v64
	v_add_f32_e32 v64, v70, v64
	v_pk_mul_f32 v[92:93], v[74:75], v[74:75]
	v_add_f32_e32 v64, v71, v64
	v_add_f32_e32 v64, v92, v64
	v_pk_mul_f32 v[94:95], v[82:83], v[82:83]
	v_add_f32_e32 v64, v93, v64
	v_add_f32_e32 v64, v94, v64
	v_pk_mul_f32 v[96:97], v[84:85], v[84:85]
	v_add_f32_e32 v64, v95, v64
	v_add_f32_e32 v64, v96, v64
	v_lshlrev_b32_e32 v88, 16, v89
	v_and_b32_e32 v89, 0xffff0000, v89
	v_pk_mul_f32 v[98:99], v[86:87], v[86:87]
	v_add_f32_e32 v64, v97, v64
	v_pk_add_f32 v[88:89], v[66:67], v[88:89]
	v_add_f32_e32 v64, v98, v64
	v_pk_mul_f32 v[100:101], v[88:89], v[88:89]
	v_add_f32_e32 v64, v99, v64
	v_add_f32_e32 v64, v100, v64
	v_add_f32_e32 v64, v101, v64
	ds_bpermute_b32 v65, v150, v64
	v_cvt_pk_bf16_f32 v66, v76, v77
	v_cvt_pk_bf16_f32 v67, v78, v79
	v_cvt_pk_bf16_f32 v68, v72, v73
	v_cvt_pk_bf16_f32 v69, v74, v75
	s_waitcnt lgkmcnt(0)
	v_add_f32_e32 v64, v64, v65
	ds_bpermute_b32 v65, v149, v64
	v_cvt_pk_bf16_f32 v70, v82, v83
	v_cvt_pk_bf16_f32 v71, v84, v85
	v_cvt_pk_bf16_f32 v72, v86, v87
	v_cvt_pk_bf16_f32 v73, v88, v89
	s_nop 1
	v_permlane16_swap_b32_e32 v66, v70
	v_permlane16_swap_b32_e32 v67, v71
	v_permlane16_swap_b32_e32 v68, v72
	v_permlane16_swap_b32_e32 v69, v73
	v_permlane32_swap_b32_e32 v66, v70
	v_permlane32_swap_b32_e32 v67, v71
	v_permlane32_swap_b32_e32 v68, v72
	v_permlane32_swap_b32_e32 v69, v73
	v_lshl_add_u64 v[238:239], v[90:91], 0, v[236:237]
	global_store_dwordx4 v[238:239], v[66:69], off
	global_store_dwordx4 v[238:239], v[70:73], off offset:64
	s_and_saveexec_b64 s[4:5], s[6:7]
	s_cbranch_execz .LBB0_1563
	s_waitcnt lgkmcnt(0)
	v_add_f32_e32 v66, v64, v65
	v_lshlrev_b64 v[64:65], 6, v[80:81]
	v_lshl_add_u64 v[64:65], s[14:15], 0, v[64:65]
	v_lshl_add_u64 v[64:65], s[26:27], 2, v[64:65]
	s_lshl_b32 s8, s40, 2
	v_lshl_add_u64 v[64:65], v[64:65], 0, s[8:9]
	global_store_dword v[64:65], v66, off
.LBB0_1563:
	s_or_b64 exec, exec, s[4:5]
	v_add_u32_e32 v64, 0x80, v140
	s_waitcnt lgkmcnt(0)
	v_ashrrev_i32_e32 v65, 31, v64
	v_lshlrev_b64 v[66:67], 11, v[64:65]
	v_lshl_add_u64 v[66:67], s[12:13], 0, v[66:67]
	v_lshl_add_u64 v[74:75], v[138:139], 1, v[66:67]
	v_lshl_add_u64 v[234:235], v[74:75], 0, v[236:237]
	global_load_dwordx4 v[66:69], v[234:235], off
	global_load_dwordx4 v[70:73], v[234:235], off offset:64
	s_waitcnt vmcnt(0)
	v_permlane32_swap_b32_e32 v66, v70
	v_permlane32_swap_b32_e32 v67, v71
	v_permlane32_swap_b32_e32 v68, v72
	v_permlane32_swap_b32_e32 v69, v73
	v_permlane16_swap_b32_e32 v66, v70
	v_permlane16_swap_b32_e32 v67, v71
	v_permlane16_swap_b32_e32 v68, v72
	v_permlane16_swap_b32_e32 v69, v73
	v_lshlrev_b32_e32 v76, 16, v66
	v_and_b32_e32 v77, 0xffff0000, v66
	v_lshlrev_b32_e32 v66, 16, v67
	v_and_b32_e32 v67, 0xffff0000, v67
	v_lshlrev_b32_e32 v78, 16, v68
	v_and_b32_e32 v79, 0xffff0000, v68
	v_lshlrev_b32_e32 v68, 16, v69
	v_and_b32_e32 v69, 0xffff0000, v69
	s_waitcnt vmcnt(0)
	v_lshlrev_b32_e32 v80, 16, v70
	v_and_b32_e32 v81, 0xffff0000, v70
	v_lshlrev_b32_e32 v70, 16, v71
	v_and_b32_e32 v71, 0xffff0000, v71
	v_lshlrev_b32_e32 v82, 16, v72
	v_and_b32_e32 v83, 0xffff0000, v72
	v_pk_add_f32 v[60:61], v[60:61], v[76:77]
	v_pk_add_f32 v[62:63], v[62:63], v[66:67]
	v_pk_add_f32 v[58:59], v[58:59], v[68:69]
	v_pk_add_f32 v[68:69], v[54:55], v[70:71]
	v_pk_add_f32 v[70:71], v[48:49], v[82:83]
	v_pk_mul_f32 v[48:49], v[60:61], v[60:61]
	v_pk_add_f32 v[66:67], v[52:53], v[80:81]
	v_pk_mul_f32 v[52:53], v[62:63], v[62:63]
	v_add_f32_e32 v48, v48, v49
	v_pk_add_f32 v[56:57], v[56:57], v[78:79]
	v_add_f32_e32 v48, v52, v48
	v_pk_mul_f32 v[54:55], v[56:57], v[56:57]
	v_add_f32_e32 v48, v53, v48
	v_add_f32_e32 v48, v54, v48
	v_pk_mul_f32 v[76:77], v[58:59], v[58:59]
	v_add_f32_e32 v48, v55, v48
	v_add_f32_e32 v48, v76, v48
	v_pk_mul_f32 v[78:79], v[66:67], v[66:67]
	v_add_f32_e32 v48, v77, v48
	v_add_f32_e32 v48, v78, v48
	v_pk_mul_f32 v[80:81], v[68:69], v[68:69]
	v_add_f32_e32 v48, v79, v48
	v_add_f32_e32 v48, v80, v48
	v_lshlrev_b32_e32 v72, 16, v73
	v_and_b32_e32 v73, 0xffff0000, v73
	v_pk_mul_f32 v[82:83], v[70:71], v[70:71]
	v_add_f32_e32 v48, v81, v48
	v_pk_add_f32 v[72:73], v[50:51], v[72:73]
	v_add_f32_e32 v48, v82, v48
	v_pk_mul_f32 v[84:85], v[72:73], v[72:73]
	v_add_f32_e32 v48, v83, v48
	v_add_f32_e32 v48, v84, v48
	v_add_f32_e32 v48, v85, v48
	ds_bpermute_b32 v49, v150, v48
	v_cvt_pk_bf16_f32 v50, v60, v61
	v_cvt_pk_bf16_f32 v51, v62, v63
	v_cvt_pk_bf16_f32 v52, v56, v57
	v_cvt_pk_bf16_f32 v53, v58, v59
	s_waitcnt lgkmcnt(0)
	v_add_f32_e32 v48, v48, v49
	ds_bpermute_b32 v49, v149, v48
	v_cvt_pk_bf16_f32 v54, v66, v67
	v_cvt_pk_bf16_f32 v55, v68, v69
	v_cvt_pk_bf16_f32 v56, v70, v71
	v_cvt_pk_bf16_f32 v57, v72, v73
	s_nop 1
	v_permlane16_swap_b32_e32 v50, v54
	v_permlane16_swap_b32_e32 v51, v55
	v_permlane16_swap_b32_e32 v52, v56
	v_permlane16_swap_b32_e32 v53, v57
	v_permlane32_swap_b32_e32 v50, v54
	v_permlane32_swap_b32_e32 v51, v55
	v_permlane32_swap_b32_e32 v52, v56
	v_permlane32_swap_b32_e32 v53, v57
	v_lshl_add_u64 v[238:239], v[74:75], 0, v[236:237]
	global_store_dwordx4 v[238:239], v[50:53], off
	global_store_dwordx4 v[238:239], v[54:57], off offset:64
	s_and_saveexec_b64 s[4:5], s[6:7]
	s_cbranch_execz .LBB0_1565
	s_waitcnt lgkmcnt(0)
	v_add_f32_e32 v50, v48, v49
	v_lshlrev_b64 v[48:49], 6, v[64:65]
	v_lshl_add_u64 v[48:49], s[14:15], 0, v[48:49]
	v_lshl_add_u64 v[48:49], s[26:27], 2, v[48:49]
	s_lshl_b32 s8, s40, 2
	v_lshl_add_u64 v[48:49], v[48:49], 0, s[8:9]
	global_store_dword v[48:49], v50, off
.LBB0_1565:
	s_or_b64 exec, exec, s[4:5]
	v_add_u32_e32 v48, 0x90, v140
	s_waitcnt lgkmcnt(0)
	v_ashrrev_i32_e32 v49, 31, v48
	v_lshlrev_b64 v[50:51], 11, v[48:49]
	v_lshl_add_u64 v[50:51], s[12:13], 0, v[50:51]
	v_lshl_add_u64 v[58:59], v[138:139], 1, v[50:51]
	v_lshl_add_u64 v[234:235], v[58:59], 0, v[236:237]
	global_load_dwordx4 v[50:53], v[234:235], off
	global_load_dwordx4 v[54:57], v[234:235], off offset:64
	s_waitcnt vmcnt(0)
	v_permlane32_swap_b32_e32 v50, v54
	v_permlane32_swap_b32_e32 v51, v55
	v_permlane32_swap_b32_e32 v52, v56
	v_permlane32_swap_b32_e32 v53, v57
	v_permlane16_swap_b32_e32 v50, v54
	v_permlane16_swap_b32_e32 v51, v55
	v_permlane16_swap_b32_e32 v52, v56
	v_permlane16_swap_b32_e32 v53, v57
	v_lshlrev_b32_e32 v60, 16, v50
	v_and_b32_e32 v61, 0xffff0000, v50
	v_lshlrev_b32_e32 v50, 16, v51
	v_and_b32_e32 v51, 0xffff0000, v51
	v_lshlrev_b32_e32 v62, 16, v52
	v_and_b32_e32 v63, 0xffff0000, v52
	v_lshlrev_b32_e32 v52, 16, v53
	v_and_b32_e32 v53, 0xffff0000, v53
	s_waitcnt vmcnt(0)
	v_lshlrev_b32_e32 v64, 16, v54
	v_and_b32_e32 v65, 0xffff0000, v54
	v_lshlrev_b32_e32 v54, 16, v55
	v_and_b32_e32 v55, 0xffff0000, v55
	v_lshlrev_b32_e32 v66, 16, v56
	v_and_b32_e32 v67, 0xffff0000, v56
	v_pk_add_f32 v[44:45], v[44:45], v[60:61]
	v_pk_add_f32 v[46:47], v[46:47], v[50:51]
	v_pk_add_f32 v[42:43], v[42:43], v[52:53]
	v_pk_add_f32 v[52:53], v[38:39], v[54:55]
	v_pk_add_f32 v[54:55], v[32:33], v[66:67]
	v_pk_mul_f32 v[32:33], v[44:45], v[44:45]
	v_pk_add_f32 v[50:51], v[36:37], v[64:65]
	v_pk_mul_f32 v[36:37], v[46:47], v[46:47]
	v_add_f32_e32 v32, v32, v33
	v_pk_add_f32 v[40:41], v[40:41], v[62:63]
	v_add_f32_e32 v32, v36, v32
	v_pk_mul_f32 v[38:39], v[40:41], v[40:41]
	v_add_f32_e32 v32, v37, v32
	v_add_f32_e32 v32, v38, v32
	v_pk_mul_f32 v[60:61], v[42:43], v[42:43]
	v_add_f32_e32 v32, v39, v32
	v_add_f32_e32 v32, v60, v32
	v_pk_mul_f32 v[62:63], v[50:51], v[50:51]
	v_add_f32_e32 v32, v61, v32
	v_add_f32_e32 v32, v62, v32
	v_pk_mul_f32 v[64:65], v[52:53], v[52:53]
	v_add_f32_e32 v32, v63, v32
	v_add_f32_e32 v32, v64, v32
	v_lshlrev_b32_e32 v56, 16, v57
	v_and_b32_e32 v57, 0xffff0000, v57
	v_pk_mul_f32 v[66:67], v[54:55], v[54:55]
	v_add_f32_e32 v32, v65, v32
	v_pk_add_f32 v[56:57], v[34:35], v[56:57]
	v_add_f32_e32 v32, v66, v32
	v_pk_mul_f32 v[68:69], v[56:57], v[56:57]
	v_add_f32_e32 v32, v67, v32
	v_add_f32_e32 v32, v68, v32
	v_add_f32_e32 v32, v69, v32
	ds_bpermute_b32 v33, v150, v32
	v_cvt_pk_bf16_f32 v34, v44, v45
	v_cvt_pk_bf16_f32 v35, v46, v47
	v_cvt_pk_bf16_f32 v36, v40, v41
	v_cvt_pk_bf16_f32 v37, v42, v43
	s_waitcnt lgkmcnt(0)
	v_add_f32_e32 v32, v32, v33
	ds_bpermute_b32 v33, v149, v32
	v_cvt_pk_bf16_f32 v38, v50, v51
	v_cvt_pk_bf16_f32 v39, v52, v53
	v_cvt_pk_bf16_f32 v40, v54, v55
	v_cvt_pk_bf16_f32 v41, v56, v57
	s_nop 1
	v_permlane16_swap_b32_e32 v34, v38
	v_permlane16_swap_b32_e32 v35, v39
	v_permlane16_swap_b32_e32 v36, v40
	v_permlane16_swap_b32_e32 v37, v41
	v_permlane32_swap_b32_e32 v34, v38
	v_permlane32_swap_b32_e32 v35, v39
	v_permlane32_swap_b32_e32 v36, v40
	v_permlane32_swap_b32_e32 v37, v41
	v_lshl_add_u64 v[238:239], v[58:59], 0, v[236:237]
	global_store_dwordx4 v[238:239], v[34:37], off
	global_store_dwordx4 v[238:239], v[38:41], off offset:64
	s_and_saveexec_b64 s[4:5], s[6:7]
	s_cbranch_execz .LBB0_1567
	s_waitcnt lgkmcnt(0)
	v_add_f32_e32 v34, v32, v33
	v_lshlrev_b64 v[32:33], 6, v[48:49]
	v_lshl_add_u64 v[32:33], s[14:15], 0, v[32:33]
	v_lshl_add_u64 v[32:33], s[26:27], 2, v[32:33]
	s_lshl_b32 s8, s40, 2
	v_lshl_add_u64 v[32:33], v[32:33], 0, s[8:9]
	global_store_dword v[32:33], v34, off
.LBB0_1567:
	s_or_b64 exec, exec, s[4:5]
	v_add_u32_e32 v32, 0xa0, v140
	s_waitcnt lgkmcnt(0)
	v_ashrrev_i32_e32 v33, 31, v32
	v_lshlrev_b64 v[34:35], 11, v[32:33]
	v_lshl_add_u64 v[34:35], s[12:13], 0, v[34:35]
	v_lshl_add_u64 v[42:43], v[138:139], 1, v[34:35]
	v_lshl_add_u64 v[234:235], v[42:43], 0, v[236:237]
	global_load_dwordx4 v[34:37], v[234:235], off
	global_load_dwordx4 v[38:41], v[234:235], off offset:64
	s_waitcnt vmcnt(0)
	v_permlane32_swap_b32_e32 v34, v38
	v_permlane32_swap_b32_e32 v35, v39
	v_permlane32_swap_b32_e32 v36, v40
	v_permlane32_swap_b32_e32 v37, v41
	v_permlane16_swap_b32_e32 v34, v38
	v_permlane16_swap_b32_e32 v35, v39
	v_permlane16_swap_b32_e32 v36, v40
	v_permlane16_swap_b32_e32 v37, v41
	v_lshlrev_b32_e32 v44, 16, v34
	v_and_b32_e32 v45, 0xffff0000, v34
	v_lshlrev_b32_e32 v34, 16, v35
	v_and_b32_e32 v35, 0xffff0000, v35
	v_lshlrev_b32_e32 v46, 16, v36
	v_and_b32_e32 v47, 0xffff0000, v36
	v_lshlrev_b32_e32 v36, 16, v37
	v_and_b32_e32 v37, 0xffff0000, v37
	s_waitcnt vmcnt(0)
	v_lshlrev_b32_e32 v48, 16, v38
	v_and_b32_e32 v49, 0xffff0000, v38
	v_lshlrev_b32_e32 v38, 16, v39
	v_and_b32_e32 v39, 0xffff0000, v39
	v_lshlrev_b32_e32 v50, 16, v40
	v_and_b32_e32 v51, 0xffff0000, v40
	v_pk_add_f32 v[28:29], v[28:29], v[44:45]
	v_pk_add_f32 v[30:31], v[30:31], v[34:35]
	v_pk_add_f32 v[26:27], v[26:27], v[36:37]
	v_pk_add_f32 v[36:37], v[22:23], v[38:39]
	v_pk_add_f32 v[38:39], v[16:17], v[50:51]
	v_pk_mul_f32 v[16:17], v[28:29], v[28:29]
	v_pk_add_f32 v[34:35], v[20:21], v[48:49]
	v_pk_mul_f32 v[20:21], v[30:31], v[30:31]
	v_add_f32_e32 v16, v16, v17
	v_pk_add_f32 v[24:25], v[24:25], v[46:47]
	v_add_f32_e32 v16, v20, v16
	v_pk_mul_f32 v[22:23], v[24:25], v[24:25]
	v_add_f32_e32 v16, v21, v16
	v_add_f32_e32 v16, v22, v16
	v_pk_mul_f32 v[44:45], v[26:27], v[26:27]
	v_add_f32_e32 v16, v23, v16
	v_add_f32_e32 v16, v44, v16
	v_pk_mul_f32 v[46:47], v[34:35], v[34:35]
	v_add_f32_e32 v16, v45, v16
	v_add_f32_e32 v16, v46, v16
	v_pk_mul_f32 v[48:49], v[36:37], v[36:37]
	v_add_f32_e32 v16, v47, v16
	v_add_f32_e32 v16, v48, v16
	v_lshlrev_b32_e32 v40, 16, v41
	v_and_b32_e32 v41, 0xffff0000, v41
	v_pk_mul_f32 v[50:51], v[38:39], v[38:39]
	v_add_f32_e32 v16, v49, v16
	v_pk_add_f32 v[40:41], v[18:19], v[40:41]
	v_add_f32_e32 v16, v50, v16
	v_pk_mul_f32 v[52:53], v[40:41], v[40:41]
	v_add_f32_e32 v16, v51, v16
	v_add_f32_e32 v16, v52, v16
	v_add_f32_e32 v16, v53, v16
	ds_bpermute_b32 v17, v150, v16
	v_cvt_pk_bf16_f32 v18, v28, v29
	v_cvt_pk_bf16_f32 v19, v30, v31
	v_cvt_pk_bf16_f32 v20, v24, v25
	v_cvt_pk_bf16_f32 v21, v26, v27
	s_waitcnt lgkmcnt(0)
	v_add_f32_e32 v16, v16, v17
	ds_bpermute_b32 v17, v149, v16
	v_cvt_pk_bf16_f32 v22, v34, v35
	v_cvt_pk_bf16_f32 v23, v36, v37
	v_cvt_pk_bf16_f32 v24, v38, v39
	v_cvt_pk_bf16_f32 v25, v40, v41
	s_nop 1
	v_permlane16_swap_b32_e32 v18, v22
	v_permlane16_swap_b32_e32 v19, v23
	v_permlane16_swap_b32_e32 v20, v24
	v_permlane16_swap_b32_e32 v21, v25
	v_permlane32_swap_b32_e32 v18, v22
	v_permlane32_swap_b32_e32 v19, v23
	v_permlane32_swap_b32_e32 v20, v24
	v_permlane32_swap_b32_e32 v21, v25
	v_lshl_add_u64 v[238:239], v[42:43], 0, v[236:237]
	global_store_dwordx4 v[238:239], v[18:21], off
	global_store_dwordx4 v[238:239], v[22:25], off offset:64
	s_and_saveexec_b64 s[4:5], s[6:7]
	s_cbranch_execz .LBB0_1569
	s_waitcnt lgkmcnt(0)
	v_add_f32_e32 v18, v16, v17
	v_lshlrev_b64 v[16:17], 6, v[32:33]
	v_lshl_add_u64 v[16:17], s[14:15], 0, v[16:17]
	v_lshl_add_u64 v[16:17], s[26:27], 2, v[16:17]
	s_lshl_b32 s8, s40, 2
	v_lshl_add_u64 v[16:17], v[16:17], 0, s[8:9]
	global_store_dword v[16:17], v18, off
.LBB0_1569:
	s_or_b64 exec, exec, s[4:5]
	v_add_u32_e32 v16, 0xb0, v140
	s_waitcnt lgkmcnt(0)
	v_ashrrev_i32_e32 v17, 31, v16
	v_lshlrev_b64 v[18:19], 11, v[16:17]
	v_lshl_add_u64 v[18:19], s[12:13], 0, v[18:19]
	v_lshl_add_u64 v[26:27], v[138:139], 1, v[18:19]
	v_lshl_add_u64 v[234:235], v[26:27], 0, v[236:237]
	global_load_dwordx4 v[18:21], v[234:235], off
	global_load_dwordx4 v[22:25], v[234:235], off offset:64
	s_waitcnt vmcnt(0)
	v_permlane32_swap_b32_e32 v18, v22
	v_permlane32_swap_b32_e32 v19, v23
	v_permlane32_swap_b32_e32 v20, v24
	v_permlane32_swap_b32_e32 v21, v25
	v_permlane16_swap_b32_e32 v18, v22
	v_permlane16_swap_b32_e32 v19, v23
	v_permlane16_swap_b32_e32 v20, v24
	v_permlane16_swap_b32_e32 v21, v25
	v_lshlrev_b32_e32 v28, 16, v18
	v_and_b32_e32 v29, 0xffff0000, v18
	v_lshlrev_b32_e32 v18, 16, v19
	v_and_b32_e32 v19, 0xffff0000, v19
	v_lshlrev_b32_e32 v30, 16, v20
	v_and_b32_e32 v31, 0xffff0000, v20
	v_lshlrev_b32_e32 v20, 16, v21
	v_and_b32_e32 v21, 0xffff0000, v21
	s_waitcnt vmcnt(0)
	v_lshlrev_b32_e32 v32, 16, v22
	v_and_b32_e32 v33, 0xffff0000, v22
	v_lshlrev_b32_e32 v22, 16, v23
	v_and_b32_e32 v23, 0xffff0000, v23
	v_lshlrev_b32_e32 v34, 16, v24
	v_and_b32_e32 v35, 0xffff0000, v24
	v_pk_add_f32 v[12:13], v[12:13], v[28:29]
	v_pk_add_f32 v[14:15], v[14:15], v[18:19]
	v_pk_add_f32 v[10:11], v[10:11], v[20:21]
	v_pk_add_f32 v[20:21], v[6:7], v[22:23]
	v_pk_add_f32 v[22:23], v[0:1], v[34:35]
	v_pk_mul_f32 v[0:1], v[12:13], v[12:13]
	v_pk_add_f32 v[18:19], v[4:5], v[32:33]
	v_pk_mul_f32 v[4:5], v[14:15], v[14:15]
	v_add_f32_e32 v0, v0, v1
	v_pk_add_f32 v[8:9], v[8:9], v[30:31]
	v_add_f32_e32 v0, v4, v0
	v_pk_mul_f32 v[6:7], v[8:9], v[8:9]
	v_add_f32_e32 v0, v5, v0
	v_add_f32_e32 v0, v6, v0
	v_pk_mul_f32 v[28:29], v[10:11], v[10:11]
	v_add_f32_e32 v0, v7, v0
	v_add_f32_e32 v0, v28, v0
	v_pk_mul_f32 v[30:31], v[18:19], v[18:19]
	v_add_f32_e32 v0, v29, v0
	v_add_f32_e32 v0, v30, v0
	v_pk_mul_f32 v[32:33], v[20:21], v[20:21]
	v_add_f32_e32 v0, v31, v0
	v_add_f32_e32 v0, v32, v0
	v_lshlrev_b32_e32 v24, 16, v25
	v_and_b32_e32 v25, 0xffff0000, v25
	v_pk_mul_f32 v[34:35], v[22:23], v[22:23]
	v_add_f32_e32 v0, v33, v0
	v_pk_add_f32 v[24:25], v[2:3], v[24:25]
	v_add_f32_e32 v0, v34, v0
	v_pk_mul_f32 v[36:37], v[24:25], v[24:25]
	v_add_f32_e32 v0, v35, v0
	v_add_f32_e32 v0, v36, v0
	v_add_f32_e32 v0, v37, v0
	ds_bpermute_b32 v1, v150, v0
	v_cvt_pk_bf16_f32 v2, v12, v13
	v_cvt_pk_bf16_f32 v3, v14, v15
	v_cvt_pk_bf16_f32 v4, v8, v9
	v_cvt_pk_bf16_f32 v5, v10, v11
	s_waitcnt lgkmcnt(0)
	v_add_f32_e32 v0, v0, v1
	ds_bpermute_b32 v1, v149, v0
	v_cvt_pk_bf16_f32 v6, v18, v19
	v_cvt_pk_bf16_f32 v7, v20, v21
	v_cvt_pk_bf16_f32 v8, v22, v23
	v_cvt_pk_bf16_f32 v9, v24, v25
	s_nop 1
	v_permlane16_swap_b32_e32 v2, v6
	v_permlane16_swap_b32_e32 v3, v7
	v_permlane16_swap_b32_e32 v4, v8
	v_permlane16_swap_b32_e32 v5, v9
	v_permlane32_swap_b32_e32 v2, v6
	v_permlane32_swap_b32_e32 v3, v7
	v_permlane32_swap_b32_e32 v4, v8
	v_permlane32_swap_b32_e32 v5, v9
	v_lshl_add_u64 v[238:239], v[26:27], 0, v[236:237]
	global_store_dwordx4 v[238:239], v[2:5], off
	global_store_dwordx4 v[238:239], v[6:9], off offset:64
	s_and_saveexec_b64 s[4:5], s[6:7]
	s_cbranch_execz .LBB0_1571
	s_waitcnt lgkmcnt(0)
	v_add_f32_e32 v2, v0, v1
	v_lshlrev_b64 v[0:1], 6, v[16:17]
	v_lshl_add_u64 v[0:1], s[14:15], 0, v[0:1]
	v_lshl_add_u64 v[0:1], s[26:27], 2, v[0:1]
	s_lshl_b32 s8, s40, 2
	v_lshl_add_u64 v[0:1], v[0:1], 0, s[8:9]
	global_store_dword v[0:1], v2, off
